# stagger odd-L workgroups by one s_sleep 100 (~3us) at the start of 13 GEMM phases, on top of v19
# speedup vs baseline: 1.0282x; 1.0013x over previous
; template <bool AF32>
; DI void phase_inproj_impl(const void* A, int lda, int nk, const bf16_t* Bt, int ntn, int mixer, const Params& P, unsigned char* smem, int L, int G) {
;   bf16_t* big = (bf16_t*)(P.ws + OFF_BIG);
;   float* mstat = (float*)(P.ws + OFF_MSTAT);
;   const float2* cs64 = (const float2*)(P.ws + OFF_CS64);
;   const float2* cs32 = (const float2*)(P.ws + OFF_CS32);
;   const int ntiles = 256 * ntn;
;   const int ldb = nk * 64;
;   GR R;
;   ARowPlain arb{(const bf16_t*)A, lda};
;   const int pw = ntn > 5 ? 5 : ntn;
;   if (L < ntiles) { int mt, nt; panel_tile(L, ntn, pw, mt, nt); gemm_first<false>(R, arb, Bt, ldb, mt * 256, nt * 256); }
.LBB0_237:
	s_or_b64 exec, exec, s[0:1]
	s_add_u32 s80, s72, 0x4f68800
	s_addc_u32 s81, s73, 0
	s_cmpk_lt_i32 s70, 0xa00
	s_cselect_b64 s[0:1], -1, 0
	s_cmpk_gt_i32 s70, 0x9ff
	s_mul_hi_i32 s2, s70, 0x66666667
	s_waitcnt lgkmcnt(0)
	s_barrier
	s_cselect_b32 s99, 1, 0
	s_bitcmp1_b32 s70, 0
	s_cbranch_scc0 .Lstg_skip_1
	s_sleep 100

; template <bool XF32>
; DI void phase_outproj(const Params& P, int layer, const void* xres, const bf16_t* og, unsigned char* smem, int L, int G) {
;   bf16_t* Sb = (bf16_t*)(P.ws + OFF_BIG);
;   float* stats = (float*)(P.ws + OFF_STATS);
;   const bf16_t* Bt = (const bf16_t*)(P.ws + OFF_WOUTT) + (size_t)layer * 1024 * 1024;
;   bf16_t* stg = (bf16_t*)smem;
;   GR R;
;   ARowPlain ar{og, 1024};
;   if (L < 256 * 4) gemm_first<false>(R, ar, Bt, 1024, (L >> 2) * 256, (L & 3) * 256);
;   for (int t = L; t < 256 * 4; t += G) {
.LBB0_404:
	s_or_b64 exec, exec, s[0:1]
	s_add_u32 s78, s72, 0x4368800
	s_addc_u32 s79, s73, 0
	s_cmpk_lt_i32 s70, 0x400
	s_cselect_b64 s[0:1], -1, 0
	s_cmpk_gt_i32 s70, 0x3ff
	s_waitcnt lgkmcnt(0)
	s_barrier
	s_cselect_b32 s99, 1, 0
	s_bitcmp1_b32 s70, 0
	s_cbranch_scc0 .Lstg_skip_3
	s_sleep 100

; template <bool LAST>
; DI void phase_gate(const Params& P, int layer, unsigned char* smem, int L, int G) {
;   const bf16_t* Sb = (const bf16_t*)(P.ws + OFF_BIG);
;   const bf16_t* PPb = (const bf16_t*)(P.ws + OFF_BIG) + BG_PP;
;   const float* stats = (const float*)(P.ws + OFF_STATS);
;   const bf16_t* Bg = (const bf16_t*)(P.ws + OFF_PGT) + (size_t)layer * 1024 * 1024;
;   const float* c1 = (const float*)(P.ws + OFF_C1) + layer * 1024;
;   const float* c2 = (const float*)(P.ws + OFF_C2) + layer * 1024;
;   const float* lg = P.ln_g + layer * 1024; const float* lb = P.ln_b + layer * 1024;
;   bf16_t* xb = (bf16_t*)(P.ws + OFF_XB);
;   float* rowA = (float*)(smem + LDS_ROW_OFF); float* rowB = rowA + 256;
;   float* vecL = (float*)(smem + LDS_VEC_OFF);
;   bf16_t* stg = (bf16_t*)smem;
;   GR R;
;   ARowPlain ars{Sb, 1024};
;   for (int t = L; t < 256 * 4; t += G) {
.LBB0_477:
	s_or_b64 exec, exec, s[2:3]
	s_waitcnt lgkmcnt(0)
	v_cndmask_b32_e64 v0, 0, 1, s[0:1]
	s_add_u32 s66, s72, 0x14f68800
	v_cmp_ne_u32_e64 s[2:3], 1, v0
	s_addc_u32 s67, s73, 0
	s_andn2_b64 vcc, exec, s[0:1]
	v_writelane_b32 v246, s2, 30
	s_barrier
	s_cselect_b32 s99, 1, 0
	s_bitcmp1_b32 s70, 0
	s_cbranch_scc0 .Lstg_skip_4
	s_sleep 100

; template <bool AF32>
; DI void phase_inproj_impl(const void* A, int lda, int nk, const bf16_t* Bt, int ntn, int mixer, const Params& P, unsigned char* smem, int L, int G) {
;   bf16_t* big = (bf16_t*)(P.ws + OFF_BIG);
;   float* mstat = (float*)(P.ws + OFF_MSTAT);
;   const float2* cs64 = (const float2*)(P.ws + OFF_CS64);
;   const float2* cs32 = (const float2*)(P.ws + OFF_CS32);
;   const int ntiles = 256 * ntn;
;   const int ldb = nk * 64;
;   GR R;
;   ARowPlain arb{(const bf16_t*)A, lda};
;   const int pw = ntn > 5 ? 5 : ntn;
;   if (L < ntiles) { int mt, nt; panel_tile(L, ntn, pw, mt, nt); gemm_first<false>(R, arb, Bt, ldb, mt * 256, nt * 256); }
.LBB0_540:
	s_or_b64 exec, exec, s[0:1]
	s_cmpk_lt_i32 s70, 0x700
	s_cselect_b64 s[0:1], -1, 0
	s_cmpk_gt_i32 s70, 0x6ff
	s_waitcnt lgkmcnt(0)
	s_barrier
	s_cselect_b32 s99, 1, 0
	s_bitcmp1_b32 s70, 0
	s_cbranch_scc0 .Lstg_skip_5
	s_sleep 100

; DI int otid() { int t = threadIdx.x; asm volatile("" : "+v"(t)); return t; }
; DI void phase_mla_up(const Params& P, unsigned char* smem, int L, int G) {
;     ...
;   const int nq = 256 * 6, nkv = 256 * 8;
;   for (int t = L; t < nq + nkv; t += G) {
;     const int tid = otid();
;     const bool isq = t < nq;
;     const int tt = isq ? t : t - nq;
;     const int ntn = isq ? 6 : 8;
;     const int mt = tt / ntn, nt = tt - mt * ntn;
;     if (tid < 256) {
.LBB0_632:
	s_or_b64 exec, exec, s[0:1]
	s_cmpk_gt_i32 s70, 0xdff
	s_waitcnt lgkmcnt(0)
	s_barrier
	s_cselect_b32 s99, 1, 0
	s_bitcmp1_b32 s70, 0
	s_cbranch_scc0 .Lstg_skip_6
	s_sleep 100

; template <bool LAST>
; DI void phase_gate(const Params& P, int layer, unsigned char* smem, int L, int G) {
;   const bf16_t* Sb = (const bf16_t*)(P.ws + OFF_BIG);
;   const bf16_t* PPb = (const bf16_t*)(P.ws + OFF_BIG) + BG_PP;
;   const float* stats = (const float*)(P.ws + OFF_STATS);
;   const bf16_t* Bg = (const bf16_t*)(P.ws + OFF_PGT) + (size_t)layer * 1024 * 1024;
;   const float* c1 = (const float*)(P.ws + OFF_C1) + layer * 1024;
;   const float* c2 = (const float*)(P.ws + OFF_C2) + layer * 1024;
;   const float* lg = P.ln_g + layer * 1024; const float* lb = P.ln_b + layer * 1024;
;   bf16_t* xb = (bf16_t*)(P.ws + OFF_XB);
;   float* rowA = (float*)(smem + LDS_ROW_OFF); float* rowB = rowA + 256;
;   float* vecL = (float*)(smem + LDS_VEC_OFF);
;   bf16_t* stg = (bf16_t*)smem;
;   GR R;
;   ARowPlain ars{Sb, 1024};
;   for (int t = L; t < 256 * 4; t += G) {
.LBB0_845:
	s_or_b64 exec, exec, s[0:1]
	v_readlane_b32 s0, v246, 30
	v_readlane_b32 s1, v246, 31
	s_and_b64 vcc, exec, s[0:1]
	s_waitcnt lgkmcnt(0)
	s_barrier
	s_cselect_b32 s99, 1, 0
	s_bitcmp1_b32 s70, 0
	s_cbranch_scc0 .Lstg_skip_8
	s_sleep 100

; template <bool AF32>
; DI void phase_inproj_impl(const void* A, int lda, int nk, const bf16_t* Bt, int ntn, int mixer, const Params& P, unsigned char* smem, int L, int G) {
;   bf16_t* big = (bf16_t*)(P.ws + OFF_BIG);
;   float* mstat = (float*)(P.ws + OFF_MSTAT);
;   const float2* cs64 = (const float2*)(P.ws + OFF_CS64);
;   const float2* cs32 = (const float2*)(P.ws + OFF_CS32);
;   const int ntiles = 256 * ntn;
;   const int ldb = nk * 64;
;   GR R;
;   ARowPlain arb{(const bf16_t*)A, lda};
;   const int pw = ntn > 5 ? 5 : ntn;
;   if (L < ntiles) { int mt, nt; panel_tile(L, ntn, pw, mt, nt); gemm_first<false>(R, arb, Bt, ldb, mt * 256, nt * 256); }
.LBB0_981:
	s_or_b64 exec, exec, s[0:1]
	s_cmpk_lt_i32 s70, 0xf00
	s_cselect_b64 s[0:1], -1, 0
	s_cmpk_gt_i32 s70, 0xeff
	s_waitcnt lgkmcnt(0)
	s_barrier
	s_cselect_b32 s99, 1, 0
	s_bitcmp1_b32 s70, 0
	s_cbranch_scc0 .Lstg_skip_10
	s_sleep 100

; template <bool LAST>
; DI void phase_gate(const Params& P, int layer, unsigned char* smem, int L, int G) {
;   const bf16_t* Sb = (const bf16_t*)(P.ws + OFF_BIG);
;   const bf16_t* PPb = (const bf16_t*)(P.ws + OFF_BIG) + BG_PP;
;   const float* stats = (const float*)(P.ws + OFF_STATS);
;   const bf16_t* Bg = (const bf16_t*)(P.ws + OFF_PGT) + (size_t)layer * 1024 * 1024;
;   const float* c1 = (const float*)(P.ws + OFF_C1) + layer * 1024;
;   const float* c2 = (const float*)(P.ws + OFF_C2) + layer * 1024;
;   const float* lg = P.ln_g + layer * 1024; const float* lb = P.ln_b + layer * 1024;
;   bf16_t* xb = (bf16_t*)(P.ws + OFF_XB);
;   float* rowA = (float*)(smem + LDS_ROW_OFF); float* rowB = rowA + 256;
;   float* vecL = (float*)(smem + LDS_VEC_OFF);
;   bf16_t* stg = (bf16_t*)smem;
;   GR R;
;   ARowPlain ars{Sb, 1024};
;   for (int t = L; t < 256 * 4; t += G) {
.LBB0_1559:
	s_or_b64 exec, exec, s[0:1]
	v_readlane_b32 s0, v246, 28
	v_readlane_b32 s1, v246, 29
	s_and_b64 vcc, exec, s[0:1]
	s_waitcnt lgkmcnt(0)
	s_barrier
	s_cselect_b32 s99, 1, 0
	s_bitcmp1_b32 s70, 0
	s_cbranch_scc0 .Lstg_skip_16
	s_sleep 100
